# v31 + score work-queue ticket requested at the top of the item and published at the bottom
# speedup vs baseline: 1.0066x; 1.0066x over previous
; #define LAS __attribute__((address_space(3)))
; __device__ __forceinline__ int fresh_lane() { int ln; asm volatile("v_mbcnt_lo_u32_b32 %0, -1, 0\n\tv_mbcnt_hi_u32_b32 %0, -1, %0" : "=v"(ln)); return ln; }
; __device__ __forceinline__ int q_block(const Frame& F, int cw) {
;     volatile LAS int* slot = (volatile LAS int*)(F.lds + LDS_MISC + 64);
;     __syncthreads();
;     if (F.wave == 0 && fresh_lane() == 0) *slot = (int)__hip_atomic_fetch_add(F.ctl + cw, 1u, __ATOMIC_RELAXED, __HIP_MEMORY_SCOPE_AGENT);
;     __syncthreads();
;     return *slot;
; }
; template <unsigned MASK> __global__ void __launch_bounds__(NTHREADS, 2) fwd(Args A0) {
;     ...
;             for (int sr = 0; sr < SUBREP(0); ++sr) { for (int u = q_block(F, cwb + 0 + 2048 * sr); u < (1024 + 160); u = q_block(F, cwb + 0 + 2048 * sr)) {
;                 if (sr > 0) continue;
;                 if (u < 1024) { const int b = u >> 9, c = 63 - ((u >> 3) & 63), kc = u & 7; if (c >= 4 && kc < sel_nchunks(0, c)) score_item(F, l, 0, b, c, kc); }
;                 else { const int v = u - 1024; score_item(F, l, 1, v / 5, 0, v % 5); } } }
.LBB0_832:
	s_cmp_eq_u64 s[48:49], 0
	s_cbranch_scc1 .Lq_score_top
	s_mov_b64 s[100:101], exec
	s_mov_b64 exec, 1
	v_mov_b32_e32 v180, 1
	global_atomic_add v180, v201, v180, s[0:1] sc0
	s_mov_b64 exec, s[100:101]

; #define LAS __attribute__((address_space(3)))
; __device__ __forceinline__ int fresh_lane() { int ln; asm volatile("v_mbcnt_lo_u32_b32 %0, -1, 0\n\tv_mbcnt_hi_u32_b32 %0, -1, %0" : "=v"(ln)); return ln; }
; __device__ __forceinline__ int q_block(const Frame& F, int cw) {
;     volatile LAS int* slot = (volatile LAS int*)(F.lds + LDS_MISC + 64);
;     __syncthreads();
;     if (F.wave == 0 && fresh_lane() == 0) *slot = (int)__hip_atomic_fetch_add(F.ctl + cw, 1u, __ATOMIC_RELAXED, __HIP_MEMORY_SCOPE_AGENT);
;     __syncthreads();
;     return *slot;
; }
; template <unsigned MASK> __global__ void __launch_bounds__(NTHREADS, 2) fwd(Args A0) {
;     ...
;             for (int sr = 0; sr < SUBREP(0); ++sr) { for (int u = q_block(F, cwb + 0 + 2048 * sr); u < (1024 + 160); u = q_block(F, cwb + 0 + 2048 * sr)) {
.LBB0_886:
	s_or_b64 exec, exec, s[6:7]
	s_andn2_b64 vcc, exec, s[48:49]
	s_barrier
	s_cbranch_vccnz .LBB0_831
	s_waitcnt vmcnt(0)
	v_readfirstlane_b32 s4, v180
	v_mov_b32_e32 v1, s87
	s_nop 0
	v_mov_b32_e32 v0, s4
	ds_write_b32 v1, v0
	s_branch .LBB0_831
